# epilogue load hoists + first top-word look issued together with the neighbour progress-word look at the two dependent seams
# speedup vs baseline: 1.0025x; 1.0025x over previous
.LBB0_237:
	s_or_b64 exec, exec, s[20:21]
	v_readlane_b32 s4, v252, 25
	v_readlane_b32 s5, v252, 26
	s_andn2_b64 vcc, exec, s[4:5]
	s_cbranch_vccnz .Lpp0_load
	v_readlane_b32 s98, v253, 39
	v_readlane_b32 s99, v253, 40
	s_nop 4
	global_load_dword v242, v27, s[98:99] sc1
	v_readlane_b32 s4, v252, 27
	v_readlane_b32 s5, v252, 28
	s_nop 4
	global_load_dword v4, v27, s[4:5] sc1
	s_waitcnt vmcnt(0)
	v_cmp_lt_u32_e32 vcc, s75, v4
	s_cbranch_vccnz .LBB0_251
	s_mov_b32 s11, 1
	s_branch .LBB0_241

.LBB0_250:
	s_or_b64 exec, exec, s[20:21]
	s_branch .LBB0_251
.Lpp0_load:
	v_readlane_b32 s4, v253, 39
	v_readlane_b32 s5, v253, 40
	s_nop 4
	global_load_dword v242, v27, s[4:5] sc1
	s_waitcnt vmcnt(0)
.LBB0_251:
	v_readlane_b32 s4, v253, 39
	v_readlane_b32 s5, v253, 40
	s_waitcnt lgkmcnt(0)
	v_mul_lo_u32 v2, v3, v2
	s_nop 2
	v_mov_b32_e32 v3, v242
	v_cmp_lt_u32_e32 vcc, v3, v2
	s_and_saveexec_b64 s[20:21], vcc
	s_cbranch_execz .LBB0_263
	s_mov_b32 s11, 1
	s_mov_b64 s[28:29], 0
	s_branch .LBB0_254

.LBB0_784:
	s_or_b64 exec, exec, s[20:21]
	v_readlane_b32 s4, v251, 25
	v_readlane_b32 s5, v251, 26
	s_andn2_b64 vcc, exec, s[4:5]
	s_cbranch_vccnz .Lpp3_load
	v_readlane_b32 s98, v253, 39
	v_readlane_b32 s99, v253, 40
	s_nop 4
	global_load_dword v242, v27, s[98:99] sc1
	v_readlane_b32 s4, v251, 27
	v_readlane_b32 s5, v251, 28
	s_nop 4
	global_load_dword v4, v27, s[4:5] sc1
	s_waitcnt vmcnt(0)
	v_cmp_lt_u32_e32 vcc, 1, v4
	s_cbranch_vccnz .LBB0_798
	s_mov_b32 s8, 1
	s_branch .LBB0_788

.LBB0_798:
	v_readlane_b32 s4, v253, 39
	v_readlane_b32 s5, v253, 40
	s_waitcnt lgkmcnt(0)
	v_mul_lo_u32 v2, v3, v2
	s_nop 2
	v_mov_b32_e32 v3, v242
	v_cmp_lt_u32_e32 vcc, v3, v2
	s_and_saveexec_b64 s[20:21], vcc
	s_cbranch_execz .LBB0_810
	s_mov_b32 s8, 1
	s_mov_b64 s[26:27], 0
	s_branch .LBB0_801
